# lean11 + grid barrier: the first-arriving workgroup of each XCD issues an early buffer_wbl2 so the last arriver has less dirty data to write back
# baseline (speedup 1.0000x reference)
; __device__ __forceinline__ unsigned xb_ld(unsigned* p)              { return __hip_atomic_load(p, __ATOMIC_RELAXED, __HIP_MEMORY_SCOPE_AGENT); }
; __device__ __forceinline__ unsigned xb_add(unsigned* p, unsigned v) { return __hip_atomic_fetch_add(p, v, __ATOMIC_RELAXED, __HIP_MEMORY_SCOPE_AGENT); }
; #define XB_SPIN(cond, bar) do { unsigned _sp = 0; while (cond) { __builtin_amdgcn_s_sleep(1); \
;     if ((++_sp & 255u) == 0u) { if (xb_ld(&(bar)[XB_TMO])) break; if (_sp > XB_SPIN_CAP) { atomicAdd(&(bar)[XB_TMO], 1u); break; } } } } while (0)
; __device__ __forceinline__ void xcd_barrier(const XcdBarrier& b) {
;     ...
;         const unsigned old = xb_add(&bar[XB_XSUB(b.x)], 1u);
;         const unsigned gen = old / nloc;
;         if (old + 1u == (gen + 1u) * nloc) {
;             __builtin_amdgcn_fence(__ATOMIC_RELEASE, "agent");
;             asm volatile("s_waitcnt vmcnt(0)" ::: "memory");
;             const unsigned og = xb_add(&bar[XB_TOP], 1u);
;             const unsigned tg = og / nx;
;             if (og + 1u == (tg + 1u) * nx) xb_add(&bar[XB_TOPGEN], 1u);
;             else XB_SPIN(xb_ld(&bar[XB_TOPGEN]) == tg, bar);
;             __builtin_amdgcn_fence(__ATOMIC_ACQUIRE, "agent");
;             xb_add(&bar[XB_XGEN(b.x)], 1u);
;             asm volatile("s_waitcnt vmcnt(0)" ::: "memory");
;         } else {
;             XB_SPIN(xb_ld(&bar[XB_XGEN(b.x)]) == gen, bar);
.LBB0_1381:
	s_or_b64 exec, exec, s[8:9]
	v_cvt_f32_u32_e32 v4, v2
	s_waitcnt vmcnt(0)
	v_readfirstlane_b32 s6, v3
	v_sub_u32_e32 v3, 0, v2
	v_rcp_iflag_f32_e32 v4, v4
	v_add_u32_e32 v5, s6, v1
	v_mul_f32_e32 v4, 0x4f7ffffe, v4
	v_cvt_u32_f32_e32 v4, v4
	v_mul_lo_u32 v1, v3, v4
	v_mul_hi_u32 v1, v4, v1
	v_add_u32_e32 v1, v4, v1
	v_mul_hi_u32 v1, v5, v1
	v_mul_lo_u32 v3, v1, v2
	v_sub_u32_e32 v3, v5, v3
	v_add_u32_e32 v4, 1, v1
	v_cmp_ge_u32_e32 vcc, v3, v2
	s_nop 1
	v_cndmask_b32_e32 v1, v1, v4, vcc
	v_sub_u32_e32 v4, v3, v2
	v_cndmask_b32_e32 v3, v3, v4, vcc
	v_add_u32_e32 v4, 1, v1
	v_cmp_ge_u32_e32 vcc, v3, v2
	v_add_u32_e32 v3, 1, v5
	s_nop 0
	v_cndmask_b32_e32 v1, v1, v4, vcc
	v_mul_lo_u32 v4, v2, v1
	v_add_u32_e32 v2, v4, v2
	v_cmp_ne_u32_e32 vcc, v3, v2
	s_and_saveexec_b64 s[6:7], vcc
	s_xor_b64 s[6:7], exec, s[6:7]
	s_cbranch_execz .LBB0_1395
	v_cmp_eq_u32_e64 s[8:9], v5, v4
	s_nop 0
	s_and_b64 s[8:9], s[8:9], exec
	s_cbranch_scc0 .Lbar_notfirst
	buffer_wbl2 sc1
.Lbar_notfirst:
	s_waitcnt lgkmcnt(0)
	v_mov_b32_e32 v0, 0x2000
	global_load_dword v0, v0, s[4:5] offset:1024 sc1
	s_add_u32 s10, s4, 0x2400
	s_addc_u32 s11, s5, 0
	s_waitcnt vmcnt(0)
	v_cmp_eq_u32_e32 vcc, v0, v1
	s_and_saveexec_b64 s[8:9], vcc
	s_cbranch_execz .LBB0_1394
	s_mov_b32 s22, 1
	s_mov_b64 s[12:13], 0
	s_branch .LBB0_1385
